# scan prep: sub-normal rescue around v_log_f32 removed for logf(1+exp(.)) arguments (always >= 1, bit-identical)
# baseline (speedup 1.0000x reference)
.LBB0_207:
	v_add_f32_e32 v38, v90, v172
	v_mul_f32_e64 v39, |v38|, s72
	v_exp_f32_e32 v39, v39
	v_add_f32_e32 v0, v0, v86
	s_mov_b32 s1, 0x3f317217
	v_mov_b32_e32 v145, 0x41b17218
	v_add_f32_e32 v39, 1.0, v39
	s_mov_b32 s2, 0x7f800000
	s_mov_b32 s3, 0xf800000
	v_log_f32_e32 v39, v39
	v_mul_f32_e32 v86, 0x4f800000, v0
	v_max_f32_e64 v38, -v38, 0
	v_mul_f32_e32 v96, 0x3f317217, v39
	v_fma_f32 v96, v39, s1, -v96
	v_fmac_f32_e32 v96, 0x3377d1cf, v39
	v_fmac_f32_e32 v96, 0x3f317217, v39
	v_cmp_lt_f32_e64 vcc, |v39|, s2
	s_waitcnt lgkmcnt(4)
	v_add_f32_e32 v91, v91, v170
	v_mov_b32_e32 v167, v162
	v_cndmask_b32_e32 v39, v39, v96, vcc
	v_cmp_gt_f32_e32 vcc, s3, v0
	v_add_f32_e32 v38, v38, v39
	v_cndmask_b32_e32 v0, v0, v86, vcc
	v_sqrt_f32_e32 v39, v0
	v_sub_f32_e32 v38, -0.5, v38
	v_mul_f32_e32 v38, 0x3fb8aa3b, v38
	v_exp_f32_e32 v38, v38
	v_add_u32_e32 v86, -1, v39
	v_fma_f32 v90, -v86, v39, v0
	v_cmp_ge_f32_e64 s[48:49], 0, v90
	v_add_u32_e32 v90, 1, v39
	v_mul_f32_e32 v38, 0xbfb8aa3b, v38
	v_cndmask_b32_e64 v86, v39, v86, s[48:49]
	v_fma_f32 v39, -v90, v39, v0
	v_cmp_lt_f32_e64 s[48:49], 0, v39
	s_mov_b32 s3, 1.0
	v_add_f32_e32 v87, v87, v171
	v_cndmask_b32_e64 v39, v86, v90, s[48:49]
	v_mul_f32_e32 v86, 0x37800000, v39
	v_cndmask_b32_e32 v39, v39, v86, vcc
	v_cmp_class_f32_e32 vcc, v0, v251
	v_exp_f32_e32 v86, v38
	v_mul_f32_e64 v38, |v91|, s72
	v_cndmask_b32_e32 v0, v39, v0, vcc
	v_max_f32_e32 v0, 0x2b8cbccc, v0
	v_exp_f32_e32 v90, v38
	v_rcp_f32_e32 v184, v0
	v_pk_add_f32 v[38:39], v[168:169], s[2:3]
	v_mul_f32_e32 v87, 0xbfb8aa3b, v87
	v_add_f32_e32 v38, 1.0, v90
	v_pk_mul_f32 v[96:97], v[168:169], v[184:185]
	v_mov_b32_e32 v97, v39
	v_xor_b32_e32 v90, 0x80000000, v96
	v_log_f32_e32 v114, v38
	v_pk_mul_f32 v[38:39], v[96:97], v[166:167]
	v_exp_f32_e32 v87, v87
	v_mul_f32_e32 v96, 0x3f317217, v114
	v_fma_f32 v96, v114, s1, -v96
	v_fmac_f32_e32 v96, 0x3377d1cf, v114
	v_fmac_f32_e32 v96, 0x3f317217, v114
	v_cmp_lt_f32_e64 s[48:49], |v114|, s2
	v_max_f32_e64 v91, -v91, 0
	v_add_f32_e32 v87, 1.0, v87
	v_cndmask_b32_e64 v96, v114, v96, s[48:49]
	v_add_f32_e32 v91, v91, v96
	v_sub_f32_e32 v91, -0.5, v91
	v_mul_f32_e32 v91, 0x3fb8aa3b, v91
	v_exp_f32_e32 v91, v91
	v_rcp_f32_e32 v114, v87
	s_waitcnt lgkmcnt(2)
	v_add_f32_e32 v92, v92, v164
	v_lshlrev_b32_e32 v0, 16, v34
	v_mul_f32_e32 v87, 0xbfb8aa3b, v91
	v_add_f32_e32 v91, -1.0, v114
	v_mul_f32_e32 v117, v106, v91
	v_mul_f32_e64 v91, |v92|, s72
	v_exp_f32_e32 v91, v91
	v_pk_mul_f32 v[162:163], v[116:117], v[184:185]
	v_pk_add_f32 v[96:97], v[116:117], s[2:3]
	v_add_f32_e32 v88, v88, v165
	v_add_f32_e32 v91, 1.0, v91
	v_mov_b32_e32 v163, v97
	v_pk_mul_f32 v[96:97], v[162:163], v[114:115]
	v_log_f32_e32 v114, v91
	v_and_b32_e32 v106, 0xffff0000, v34
	v_max_f32_e64 v34, -v92, 0
	v_mul_f32_e32 v88, 0xbfb8aa3b, v88
	v_mul_f32_e32 v92, 0x3f317217, v114
	v_fma_f32 v92, v114, s1, -v92
	v_fmac_f32_e32 v92, 0x3377d1cf, v114
	v_fmac_f32_e32 v92, 0x3f317217, v114
	v_cmp_lt_f32_e64 s[48:49], |v114|, s2
	v_exp_f32_e32 v88, v88
	v_mov_b32_e32 v115, v110
	v_cndmask_b32_e64 v92, v114, v92, s[48:49]
	v_add_f32_e32 v34, v34, v92
	v_sub_f32_e32 v34, -0.5, v34
	v_mul_f32_e32 v34, 0x3fb8aa3b, v34
	v_exp_f32_e32 v34, v34
	v_add_f32_e32 v88, 1.0, v88
	v_rcp_f32_e32 v114, v88
	v_exp_f32_e32 v87, v87
	v_mul_f32_e32 v34, 0xbfb8aa3b, v34
	v_exp_f32_e32 v88, v34
	v_add_f32_e32 v34, -1.0, v114
	v_fma_f32 v117, v94, v34, 1.0
	s_waitcnt lgkmcnt(0)
	v_add_f32_e32 v34, v93, v42
	v_mul_f32_e64 v42, |v34|, s72
	v_exp_f32_e32 v42, v42
	v_max_f32_e64 v34, -v34, 0
	v_mul_f32_e64 v92, v112, -v184
	v_xor_b32_e32 v116, 0x80000000, v92
	v_add_f32_e32 v42, 1.0, v42
	v_xor_b32_e32 v91, 0x80000000, v162
	v_pk_mul_f32 v[116:117], v[116:117], v[114:115]
	v_log_f32_e32 v42, v42
	v_lshlrev_b32_e32 v162, 16, v35
	v_and_b32_e32 v94, 0xffff0000, v35
	v_mul_f32_e32 v166, v86, v0
	v_mul_f32_e32 v93, 0x3f317217, v42
	v_fma_f32 v93, v42, s1, -v93
	v_fmac_f32_e32 v93, 0x3377d1cf, v42
	v_fmac_f32_e32 v93, 0x3f317217, v42
	v_cmp_lt_f32_e64 s[48:49], |v42|, s2
	s_add_i32 s2, s19, 10
	s_and_b32 s68, s2, 1
	v_cndmask_b32_e64 v42, v42, v93, s[48:49]
	v_add_f32_e32 v34, v34, v42
	v_add_f32_e32 v42, v89, v43
	v_mul_f32_e32 v42, 0xbfb8aa3b, v42
	v_exp_f32_e32 v42, v42
	v_sub_f32_e32 v34, -0.5, v34
	v_mul_f32_e32 v34, 0x3fb8aa3b, v34
	v_exp_f32_e32 v34, v34
	v_add_f32_e32 v42, 1.0, v42
	v_rcp_f32_e32 v110, v42
	v_mul_f32_e64 v93, v113, -v184
	v_mul_f32_e32 v34, 0xbfb8aa3b, v34
	v_exp_f32_e32 v89, v34
	v_add_f32_e32 v34, -1.0, v110
	s_mul_i32 s2, s68, 0xc100
	v_fma_f32 v43, v108, v34, 1.0
	v_xor_b32_e32 v42, 0x80000000, v93
	s_add_i32 s69, s2, 16
	v_lshlrev_b32_e32 v34, 2, v126
	v_pk_mul_f32 v[112:113], v[42:43], v[110:111]
	v_add3_u32 v108, s69, v180, v34
	v_mul_f32_e32 v167, v87, v106
	v_mul_f32_e32 v168, v88, v162
	v_mul_f32_e32 v169, v89, v94
	ds_write_b128 v108, v[86:89] offset:2048
	v_mov_b32_e32 v86, v39
	v_mov_b32_e32 v87, v97
	v_mov_b32_e32 v88, v117
	v_mov_b32_e32 v89, v113
	ds_read2_b32 v[114:115], v143 offset0:68 offset1:131
	ds_write_b128 v108, v[86:89] offset:10240
	ds_write_b128 v108, v[90:93] offset:18432
	v_mov_b32_e32 v86, v38
	v_mov_b32_e32 v87, v96
	v_mov_b32_e32 v88, v116
	v_mov_b32_e32 v89, v112
	ds_write_b128 v108, v[86:89] offset:26624
	ds_write_b128 v108, v[166:169] offset:34816
	ds_write_b128 v108, v[82:85] offset:43008
	ds_read_b128 v[86:89], v189 offset:16
	ds_read_b128 v[82:85], v189 offset:2064
	ds_read_b128 v[90:93], v189 offset:4112
	ds_read2_b32 v[170:171], v183 offset0:4 offset1:68
	v_lshlrev_b32_e32 v42, 16, v44
	v_and_b32_e32 v43, 0xffff0000, v44
	v_lshlrev_b32_e32 v44, 16, v45
	s_and_b64 vcc, exec, s[46:47]
	v_and_b32_e32 v45, 0xffff0000, v45
	s_cbranch_vccnz .LBB0_213
	ds_read_b32 v34, v183 offset:1808
	v_lshlrev_b32_e32 v35, 16, v40
	v_sub_f32_e32 v35, v35, v42
	s_waitcnt lgkmcnt(0)
	v_add_f32_e32 v34, v90, v34
	v_mul_f32_e32 v34, 0xbfb8aa3b, v34
	v_exp_f32_e32 v34, v34
	s_nop 0
	v_add_f32_e32 v34, 1.0, v34
	v_rcp_f32_e32 v34, v34
	s_nop 0
	v_fmac_f32_e32 v42, v35, v34
	ds_read2_b32 v[166:167], v143 offset0:69 offset1:132
	ds_read2_b32 v[168:169], v183 offset0:5 offset1:69
	s_and_b64 vcc, exec, s[46:47]
	s_cbranch_vccz .LBB0_214

.LBB0_217:
	v_mul_f32_e32 v40, v39, v0
	s_waitcnt lgkmcnt(6)
	v_add_f32_e32 v86, v86, v170
	v_fma_f32 v107, v40, v107, 0
	v_mul_f32_e64 v40, |v86|, s72
	v_exp_f32_e32 v40, v40
	v_pk_fma_f32 v[38:39], v[38:39], v[0:1], 0 op_sel_hi:[1,0,0]
	v_mul_f32_e32 v0, v97, v106
	v_fmac_f32_e32 v107, v0, v95
	v_add_f32_e32 v40, 1.0, v40
	v_pk_fma_f32 v[38:39], v[96:97], v[106:107], v[38:39] op_sel_hi:[1,0,1]
	s_mov_b32 s2, 0x7f800000
	v_log_f32_e32 v92, v40
	v_pk_fma_f32 v[40:41], v[116:117], v[162:163], v[38:39] op_sel_hi:[1,0,1]
	v_mov_b32_e32 v106, 0x41b17218
	v_mul_f32_e32 v0, v117, v162
	v_mul_f32_e32 v38, 0x3f317217, v92
	v_fma_f32 v38, v92, s1, -v38
	v_fmac_f32_e32 v38, 0x3377d1cf, v92
	v_fmac_f32_e32 v38, 0x3f317217, v92
	v_cmp_lt_f32_e64 s[48:49], |v92|, s2
	v_fmac_f32_e32 v107, v0, v109
	v_cndmask_b32_e64 v38, v92, v38, s[48:49]
	v_max_f32_e64 v0, -v86, 0
	v_add_f32_e32 v0, v0, v38
	v_add_f32_e32 v38, v82, v171
	v_mul_f32_e32 v38, 0xbfb8aa3b, v38
	v_exp_f32_e32 v38, v38
	v_sub_f32_e32 v0, -0.5, v0
	v_mul_f32_e32 v0, 0x3fb8aa3b, v0
	v_exp_f32_e32 v39, v0
	v_add_f32_e32 v0, 1.0, v38
	v_rcp_f32_e32 v86, v0
	v_mul_f32_e32 v95, v113, v94
	v_mul_f32_e32 v38, 0xbfb8aa3b, v39
	v_pk_fma_f32 v[40:41], v[112:113], v[94:95], v[40:41] op_sel_hi:[1,0,1]
	v_add_f32_e32 v39, -1.0, v86
	v_fma_f32 v93, v114, v39, 1.0
	s_waitcnt lgkmcnt(4)
	v_add_f32_e32 v39, v87, v168
	v_mul_f32_e64 v87, |v39|, s72
	v_exp_f32_e32 v87, v87
	v_mul_f32_e64 v82, v104, -v184
	v_xor_b32_e32 v92, 0x80000000, v82
	s_waitcnt lgkmcnt(2)
	v_add_f32_e32 v88, v88, v164
	v_add_f32_e32 v87, 1.0, v87
	v_exp_f32_e32 v38, v38
	v_lshlrev_b32_e32 v0, 16, v36
	v_log_f32_e32 v94, v87
	v_mov_b32_e32 v87, v102
	v_pk_mul_f32 v[86:87], v[92:93], v[86:87]
	v_mul_f32_e32 v92, 0x3f317217, v94
	v_fma_f32 v92, v94, s1, -v92
	v_fmac_f32_e32 v92, 0x3377d1cf, v94
	v_fmac_f32_e32 v92, 0x3f317217, v94
	v_cmp_lt_f32_e64 s[48:49], |v94|, s2
	v_fmac_f32_e32 v107, v95, v115
	v_max_f32_e64 v39, -v39, 0
	v_cndmask_b32_e64 v92, v94, v92, s[48:49]
	v_mul_f32_e64 v93, |v88|, s72
	v_exp_f32_e32 v93, v93
	v_mul_f32_e32 v96, v87, v0
	v_add_f32_e32 v39, v39, v92
	v_mul_f32_e32 v92, v38, v0
	v_fmac_f32_e32 v107, v96, v167
	v_pk_fma_f32 v[96:97], v[86:87], v[0:1], v[40:41] op_sel_hi:[1,0,1]
	v_add_f32_e32 v0, 1.0, v93
	v_add_f32_e32 v83, v83, v169
	v_mul_f32_e32 v83, 0xbfb8aa3b, v83
	v_log_f32_e32 v40, v0
	v_exp_f32_e32 v83, v83
	v_and_b32_e32 v0, 0xffff0000, v36
	v_max_f32_e64 v36, -v88, 0
	v_mul_f32_e32 v41, 0x3f317217, v40
	v_fma_f32 v41, v40, s1, -v41
	v_fmac_f32_e32 v41, 0x3377d1cf, v40
	v_fmac_f32_e32 v41, 0x3f317217, v40
	v_cmp_lt_f32_e64 s[48:49], |v40|, s2
	v_sub_f32_e32 v39, -0.5, v39
	v_mul_f32_e32 v39, 0x3fb8aa3b, v39
	v_cndmask_b32_e64 v40, v40, v41, s[48:49]
	v_add_f32_e32 v36, v36, v40
	v_add_f32_e32 v40, v84, v165
	v_mul_f32_e32 v40, 0xbfb8aa3b, v40
	v_exp_f32_e32 v40, v40
	v_exp_f32_e32 v39, v39
	v_add_f32_e32 v83, 1.0, v83
	v_rcp_f32_e32 v102, v83
	v_sub_f32_e32 v36, -0.5, v36
	v_mul_f32_e32 v36, 0x3fb8aa3b, v36
	v_exp_f32_e32 v36, v36
	v_add_f32_e32 v40, 1.0, v40
	s_waitcnt lgkmcnt(0)
	v_add_f32_e32 v41, v89, v90
	v_mul_f32_e32 v39, 0xbfb8aa3b, v39
	v_rcp_f32_e32 v88, v40
	v_mul_f32_e64 v89, |v41|, s72
	v_exp_f32_e32 v39, v39
	v_add_f32_e32 v83, -1.0, v102
	v_exp_f32_e32 v90, v89
	v_fma_f32 v95, v166, v83, 1.0
	v_mul_f32_e64 v83, v105, -v184
	v_xor_b32_e32 v94, 0x80000000, v83
	v_mul_f32_e32 v36, 0xbfb8aa3b, v36
	v_pk_mul_f32 v[102:103], v[94:95], v[102:103]
	v_exp_f32_e32 v40, v36
	v_add_f32_e32 v36, -1.0, v88
	v_mul_f32_e32 v93, v39, v0
	v_fma_f32 v95, v110, v36, 1.0
	v_mul_f32_e32 v36, v103, v0
	v_pk_fma_f32 v[96:97], v[102:103], v[0:1], v[96:97] op_sel_hi:[1,0,1]
	v_add_f32_e32 v0, 1.0, v90
	v_fmac_f32_e32 v107, v36, v111
	v_max_f32_e64 v41, -v41, 0
	v_log_f32_e32 v36, v0
	v_mov_b32_e32 v89, v98
	v_mul_f32_e64 v84, v100, -v184
	v_xor_b32_e32 v94, 0x80000000, v84
	v_mul_f32_e32 v90, 0x3f317217, v36
	v_fma_f32 v90, v36, s1, -v90
	v_fmac_f32_e32 v90, 0x3377d1cf, v36
	v_fmac_f32_e32 v90, 0x3f317217, v36
	v_cmp_lt_f32_e64 s[48:49], |v36|, s2
	v_pk_mul_f32 v[88:89], v[94:95], v[88:89]
	v_lshlrev_b32_e32 v0, 16, v37
	v_cndmask_b32_e64 v36, v36, v90, s[48:49]
	v_add_f32_e32 v36, v41, v36
	v_add_f32_e32 v41, v85, v91
	v_mul_f32_e32 v41, 0xbfb8aa3b, v41
	v_exp_f32_e32 v41, v41
	v_sub_f32_e32 v36, -0.5, v36
	v_mul_f32_e32 v36, 0x3fb8aa3b, v36
	v_exp_f32_e32 v36, v36
	v_add_f32_e32 v41, 1.0, v41
	v_rcp_f32_e32 v98, v41
	v_mul_f32_e64 v85, v101, -v184
	v_mul_f32_e32 v36, 0xbfb8aa3b, v36
	v_exp_f32_e32 v41, v36
	v_add_f32_e32 v36, -1.0, v98
	v_fma_f32 v91, v34, v36, 1.0
	v_xor_b32_e32 v90, 0x80000000, v85
	v_pk_mul_f32 v[90:91], v[90:91], v[98:99]
	ds_read_b32 v98, v183 offset:1052
	v_mul_f32_e32 v34, v89, v0
	v_mul_f32_e32 v94, v40, v0
	v_fmac_f32_e32 v107, v34, v35
	v_pk_fma_f32 v[96:97], v[88:89], v[0:1], v[96:97] op_sel_hi:[1,0,1]
	v_and_b32_e32 v0, 0xffff0000, v37
	v_mov_b32_e32 v34, v87
	v_mov_b32_e32 v35, v103
	v_mov_b32_e32 v36, v89
	v_mov_b32_e32 v37, v91
	ds_write_b128 v108, v[38:41] offset:2064
	ds_write_b128 v108, v[34:37] offset:10256
	ds_write_b128 v108, v[82:85] offset:18448
	v_mul_f32_e32 v34, v91, v0
	s_waitcnt lgkmcnt(3)
	v_fmac_f32_e32 v107, v34, v98
	v_pk_fma_f32 v[34:35], v[90:91], v[0:1], v[96:97] op_sel_hi:[1,0,1]
	v_mul_f32_e32 v95, v41, v0
	v_add_f32_dpp v0, v107, v107 quad_perm:[1,0,3,2] row_mask:0xf bank_mask:0xf bound_ctrl:1
	v_mov_b32_dpp v36, v34 quad_perm:[1,0,3,2] row_mask:0xf bank_mask:0xf bound_ctrl:1
	v_mov_b32_dpp v37, v35 quad_perm:[1,0,3,2] row_mask:0xf bank_mask:0xf bound_ctrl:1
	v_pk_add_f32 v[34:35], v[34:35], v[36:37]
	v_add_f32_dpp v0, v0, v0 quad_perm:[2,3,0,1] row_mask:0xf bank_mask:0xf bound_ctrl:1
	v_mov_b32_e32 v87, v102
	v_mov_b32_dpp v36, v34 quad_perm:[2,3,0,1] row_mask:0xf bank_mask:0xf bound_ctrl:1
	v_mov_b32_dpp v37, v35 quad_perm:[2,3,0,1] row_mask:0xf bank_mask:0xf bound_ctrl:1
	v_pk_add_f32 v[34:35], v[34:35], v[36:37]
	v_mov_b32_e32 v89, v90
	v_mov_b32_dpp v38, v0 row_half_mirror row_mask:0xf bank_mask:0xf bound_ctrl:1
	v_mov_b32_dpp v36, v34 row_half_mirror row_mask:0xf bank_mask:0xf bound_ctrl:1
	v_mov_b32_dpp v37, v35 row_half_mirror row_mask:0xf bank_mask:0xf bound_ctrl:1
	ds_write_b128 v108, v[86:89] offset:26640
	ds_write_b128 v108, v[92:95] offset:34832
	ds_write_b128 v108, v[42:45] offset:43024
	s_and_saveexec_b64 s[2:3], s[42:43]
	s_cbranch_execz .LBB0_164
	v_pk_add_f32 v[34:35], v[34:35], v[36:37]
	v_lshl_add_u32 v36, s68, 7, v182
	v_add_f32_e32 v0, v0, v38
	v_add_u32_e32 v39, s69, v186
	ds_write_b32 v36, v0
	ds_write_b64 v39, v[34:35] offset:51200
	s_branch .LBB0_164
